# stick-breaking attention reads prompt K/V rows as f32 from the k_prompt/v_prompt outputs and converts per visited block; bf16 K/V copies dropped from the P7 epilogue
# speedup vs baseline: 1.2450x; 1.0024x over previous
.Lp7_epi_kv:
	s_cmp_gt_u32 s10, 63
	s_cbranch_scc1 .Lp7_epi_orig
	v_lshl_add_u32 v2, s10, 8, v240
	v_lshl_or_b32 v132, s58, 8, v242
	s_mov_b32 s16, 0x8100000
	s_cmp_gt_u32 s58, 5
	s_cselect_b32 s16, 0xe100000, s16
	s_cselect_b32 s17, 0x1800, 0
	s_cselect_b32 s14, s71, s3
	s_cselect_b32 s15, s72, s33
	s_add_u32 s12, s48, s16
	s_addc_u32 s13, s49, 0
	s_lshr_b32 s18, s17, 1
	v_bfe_u32 v138, v242, 2, 1
	v_mul_u32_u24_e32 v138, 24, v138
	v_lshl_add_u32 v138, v132, 1, v138
	v_subrev_u32_e32 v138, s18, v138
	v_lshlrev_b32_e32 v136, 2, v132
	v_subrev_u32_e32 v136, s17, v136
	v_mul_u32_u24_e32 v3, 0x1800, v2
	v_add_u32_e32 v140, v3, v136
	v_lshrrev_b32_e32 v3, 1, v3
	v_add_u32_e32 v148, v3, v138
	v_add_u32_e32 v141, 0x18000, v140
	v_add_u32_e32 v149, 0xc000, v148
	v_add_u32_e32 v142, 0x30000, v140
	v_add_u32_e32 v150, 0x18000, v148
	v_add_u32_e32 v143, 0x48000, v140
	v_add_u32_e32 v151, 0x24000, v148
	v_add_u32_e32 v144, 0xc0000, v140
	v_add_u32_e32 v152, 0x60000, v148
	v_add_u32_e32 v145, 0xd8000, v140
	v_add_u32_e32 v153, 0x6c000, v148
	v_add_u32_e32 v146, 0xf0000, v140
	v_add_u32_e32 v154, 0x78000, v148
	v_add_u32_e32 v147, 0x108000, v140
	v_add_u32_e32 v155, 0x84000, v148
	s_nop 7
	global_store_dwordx4 v140, v[128:131], s[12:13]
	global_store_dwordx4 v140, v[124:127], s[12:13] offset:64
	global_store_dwordx4 v140, v[120:123], s[12:13] offset:512
	global_store_dwordx4 v140, v[116:119], s[12:13] offset:576
	global_store_dwordx4 v141, v[112:115], s[12:13]
	global_store_dwordx4 v141, v[108:111], s[12:13] offset:64
	global_store_dwordx4 v141, v[104:107], s[12:13] offset:512
	global_store_dwordx4 v141, v[100:103], s[12:13] offset:576
	global_store_dwordx4 v142, v[96:99], s[12:13]
	global_store_dwordx4 v142, v[92:95], s[12:13] offset:64
	global_store_dwordx4 v142, v[88:91], s[12:13] offset:512
	global_store_dwordx4 v142, v[84:87], s[12:13] offset:576
	global_store_dwordx4 v143, v[80:83], s[12:13]
	global_store_dwordx4 v143, v[76:79], s[12:13] offset:64
	global_store_dwordx4 v143, v[72:75], s[12:13] offset:512
	global_store_dwordx4 v143, v[68:71], s[12:13] offset:576
	global_store_dwordx4 v144, v[64:67], s[12:13]
	global_store_dwordx4 v144, v[60:63], s[12:13] offset:64
	global_store_dwordx4 v144, v[56:59], s[12:13] offset:512
	global_store_dwordx4 v144, v[52:55], s[12:13] offset:576
	global_store_dwordx4 v145, v[48:51], s[12:13]
	global_store_dwordx4 v145, v[44:47], s[12:13] offset:64
	global_store_dwordx4 v145, v[40:43], s[12:13] offset:512
	global_store_dwordx4 v145, v[36:39], s[12:13] offset:576
	global_store_dwordx4 v146, v[32:35], s[12:13]
	global_store_dwordx4 v146, v[28:31], s[12:13] offset:64
	global_store_dwordx4 v146, v[24:27], s[12:13] offset:512
	global_store_dwordx4 v146, v[20:23], s[12:13] offset:576
	global_store_dwordx4 v147, v[16:19], s[12:13]
	global_store_dwordx4 v147, v[12:15], s[12:13] offset:64
	global_store_dwordx4 v147, v[8:11], s[12:13] offset:512
	global_store_dwordx4 v147, v[4:7], s[12:13] offset:576
	s_mov_b64 s[8:9], exec
	s_branch .LBB0_534

.LBB0_869:
	s_or_b64 exec, exec, s[52:53]
	s_add_u32 s46, s50, s46
	s_addc_u32 s47, s51, s47
	s_lshl_b64 s[44:45], s[44:45], 1
	s_add_u32 s44, s46, s44
	s_addc_u32 s45, s47, s45
	s_lshl_b64 s[22:23], s[22:23], 1
	s_add_u32 s22, s44, s22
	s_addc_u32 s23, s45, s23
	s_add_i32 s44, s60, s61
	s_add_i32 s45, s44, -2
	s_lshr_b32 s45, s45, 6
	s_cmp_gt_i32 s44, 1
	s_cselect_b32 s46, s45, 0
	s_lshl_b32 s60, s46, 6
	s_mov_b32 s101, 0
	s_cmp_eq_u32 s40, 0x40f
	s_cbranch_scc1 .Lsb_pro_bf16
	v_lshl_add_u64 v[74:75], s[18:19], 0, v[68:69]
	v_lshl_add_u64 v[76:77], s[22:23], 0, v[68:69]
	s_cmp_lg_u32 s40, 0x40f
	s_cbranch_scc1 .Lsb_pro_p
	s_sub_u32 s100, s94, 0xf0
	s_subb_u32 s101, s95, 0
	s_load_dwordx4 s[96:99], s[100:101], 0x0
	s_and_b32 s100, s57, 0xff
	s_mulk_i32 s100, 0xab
	s_lshr_b32 s100, s100, 11
	s_mul_i32 s100, s100, 0x600000
	s_lshl_b32 s101, s58, 9
	s_add_u32 s100, s100, s101
	s_waitcnt lgkmcnt(0)
	s_branch .Lsb_pro_j
.Lsb_pro_p:
	s_sub_u32 s100, s94, 0x10
	s_subb_u32 s101, s95, 0
	s_load_dwordx2 s[96:97], s[100:101], 0x0
	s_lshr_b32 s100, s59, 12
	s_mul_i32 s100, s100, 0x1800000
	s_lshl_b32 s101, s58, 9
	s_add_u32 s100, s100, s101
	s_waitcnt lgkmcnt(0)
	s_add_u32 s98, s96, 0xe100000
	s_addc_u32 s99, s97, 0
	s_add_u32 s96, s96, 0x8100000
	s_addc_u32 s97, s97, 0
.Lsb_pro_j:
	s_add_u32 s96, s96, s100
	s_addc_u32 s97, s97, 0
	s_add_u32 s98, s98, s100
	s_addc_u32 s99, s99, 0
	v_add_u32_e32 v192, s60, v234
	v_mul_u32_u24_e32 v192, 0x1800, v192
	v_lshl_add_u32 v192, v68, 1, v192
	v_add_u32_e32 v193, 0x30000, v192
	global_load_dwordx4 v[160:163], v192, s[96:97]
	global_load_dwordx4 v[164:167], v192, s[96:97] offset:16
	global_load_dwordx4 v[168:171], v192, s[98:99]
	global_load_dwordx4 v[172:175], v192, s[98:99] offset:16
	global_load_dwordx4 v[176:179], v193, s[96:97]
	global_load_dwordx4 v[180:183], v193, s[96:97] offset:16
	global_load_dwordx4 v[184:187], v193, s[98:99]
	global_load_dwordx4 v[188:191], v193, s[98:99] offset:16
	s_mov_b32 s101, 1
	s_branch .Lsb_pro_done
.Lsb_pro_bf16:
	v_or_b32_e32 v16, s60, v234
	v_min_u32_e32 v16, s40, v16
	v_mul_u32_u24_e32 v16, 0x600, v16
	v_lshl_add_u64 v[74:75], s[18:19], 0, v[68:69]
	v_lshl_add_u64 v[76:77], s[22:23], 0, v[68:69]
	v_lshlrev_b32_e32 v16, 1, v16
	v_mov_b32_e32 v17, v69
	v_lshl_add_u64 v[18:19], v[74:75], 0, v[16:17]
	v_lshl_add_u64 v[16:17], v[76:77], 0, v[16:17]
	global_load_dwordx4 v[52:55], v[16:17], off
	v_add_u32_e32 v16, s60, v83
	v_min_u32_e32 v16, s40, v16
	v_mul_u32_u24_e32 v16, 0x600, v16
	v_lshlrev_b32_e32 v16, 1, v16
	v_mov_b32_e32 v17, v69
	global_load_dwordx4 v[48:51], v[18:19], off
	v_lshl_add_u64 v[18:19], v[74:75], 0, v[16:17]
	v_lshl_add_u64 v[16:17], v[76:77], 0, v[16:17]
	global_load_dwordx4 v[56:59], v[18:19], off
	global_load_dwordx4 v[60:63], v[16:17], off
.Lsb_pro_done:
	v_add_u32_e32 v16, s61, v237
	v_or_b32_e32 v78, v16, v198
	v_mov_b32_e32 v97, 0
	v_or_b32_e32 v96, 15, v16
	v_mov_b32_e32 v73, v78
	s_mov_b64 s[44:45], 0
	v_mov_b32_e32 v98, s46
	v_mov_b32_e32 v44, 0
	v_mov_b32_e32 v45, v97
	v_mov_b32_e32 v46, v97
	v_mov_b32_e32 v47, v97
	v_mov_b32_e32 v40, 0
	v_mov_b32_e32 v41, v97
	v_mov_b32_e32 v42, v97
	v_mov_b32_e32 v43, v97
	v_mov_b32_e32 v36, 0
	v_mov_b32_e32 v37, v97
	v_mov_b32_e32 v38, v97
	v_mov_b32_e32 v39, v97
	v_mov_b32_e32 v32, 0
	v_mov_b32_e32 v33, v97
	v_mov_b32_e32 v34, v97
	v_mov_b32_e32 v35, v97
	v_mov_b32_e32 v28, 0
	v_mov_b32_e32 v29, v97
	v_mov_b32_e32 v30, v97
	v_mov_b32_e32 v31, v97
	v_mov_b32_e32 v24, 0
	v_mov_b32_e32 v25, v97
	v_mov_b32_e32 v26, v97
	v_mov_b32_e32 v27, v97
	v_mov_b32_e32 v20, 0
	v_mov_b32_e32 v21, v97
	v_mov_b32_e32 v22, v97
	v_mov_b32_e32 v23, v97
	v_mov_b32_e32 v16, 0
	v_mov_b32_e32 v17, v97
	v_mov_b32_e32 v18, v97
	v_mov_b32_e32 v19, v97
	s_branch .LBB0_871

.Lsb_nocvt:
	s_waitcnt vmcnt(2)
	ds_write_b128 v64, v[48:51]
	v_add_u32_e32 v64, v88, v80
	ds_write_b128 v64, v[52:55] offset:17408
	v_add_u32_e32 v64, v88, v82
	v_cmp_gt_i32_e32 vcc, 1, v98
	s_waitcnt vmcnt(1)
	ds_write_b128 v64, v[56:59]
	v_add_u32_e32 v64, v88, v81
	s_and_b64 vcc, exec, vcc
	s_waitcnt vmcnt(0)
	ds_write_b128 v64, v[60:63] offset:17408
	s_waitcnt lgkmcnt(0)
	s_barrier
	s_cbranch_vccnz .LBB0_873
	s_cmp_lg_u32 s40, 0x40f
	s_cbranch_scc1 .Lsb_loop_p
	s_sub_u32 s100, s94, 0xf0
	s_subb_u32 s101, s95, 0
	s_load_dwordx4 s[96:99], s[100:101], 0x0
	s_and_b32 s100, s57, 0xff
	s_mulk_i32 s100, 0xab
	s_lshr_b32 s100, s100, 11
	s_mul_i32 s100, s100, 0x600000
	s_lshl_b32 s101, s58, 9
	s_add_u32 s100, s100, s101
	s_waitcnt lgkmcnt(0)
	s_branch .Lsb_loop_j

.Lsb_loop_j:
	s_add_u32 s96, s96, s100
	s_addc_u32 s97, s97, 0
	s_add_u32 s98, s98, s100
	s_addc_u32 s99, s99, 0
	v_add_u32_e32 v192, s60, v92
	v_mul_u32_u24_e32 v192, 0x1800, v192
	v_lshl_add_u32 v192, v68, 1, v192
	v_add_u32_e32 v193, 0x30000, v192
	global_load_dwordx4 v[160:163], v192, s[96:97]
	global_load_dwordx4 v[164:167], v192, s[96:97] offset:16
	global_load_dwordx4 v[168:171], v192, s[98:99]
	global_load_dwordx4 v[172:175], v192, s[98:99] offset:16
	global_load_dwordx4 v[176:179], v193, s[96:97]
	global_load_dwordx4 v[180:183], v193, s[96:97] offset:16
	global_load_dwordx4 v[184:187], v193, s[98:99]
	global_load_dwordx4 v[188:191], v193, s[98:99] offset:16
	s_mov_b32 s101, 1
	s_branch .LBB0_873
	v_add_u32_e32 v48, s60, v92
	v_add_u32_e32 v56, s60, v91
	v_min_i32_e32 v52, s40, v48
	v_min_i32_e32 v60, s40, v56
	v_mad_u64_u32 v[48:49], s[18:19], v52, s35, v[74:75]
	v_mad_u64_u32 v[52:53], s[18:19], v52, s35, v[76:77]
	v_mad_u64_u32 v[56:57], s[18:19], v60, s35, v[74:75]
	v_mad_u64_u32 v[60:61], s[18:19], v60, s35, v[76:77]
	global_load_dwordx4 v[48:51], v[48:49], off
	s_nop 0
	global_load_dwordx4 v[52:55], v[52:53], off
	s_nop 0
	global_load_dwordx4 v[56:59], v[56:57], off
	s_nop 0
	global_load_dwordx4 v[60:63], v[60:61], off
